# phase 4 rewrite with the v_cmp -> v_cndmask wait states padded
# speedup vs baseline: 1.1529x; 1.0016x over previous
.Llin_no3:
	s_waitcnt vmcnt(8)
	v_lshlrev_b32_e32 v2, 16, v56
	v_and_b32_e32 v3, 0xffff0000, v56
	v_lshlrev_b32_e32 v4, 16, v57
	v_and_b32_e32 v5, 0xffff0000, v57
	v_lshlrev_b32_e32 v6, 16, v58
	v_and_b32_e32 v7, 0xffff0000, v58
	v_lshlrev_b32_e32 v8, 16, v59
	v_and_b32_e32 v9, 0xffff0000, v59
	v_and_b32_e32 v18, 0x7ff, v40
	v_cmp_eq_u32_e32 vcc, 0, v18
	s_nop 1
	v_cndmask_b32_e64 v72, v72, 0, vcc
	v_cndmask_b32_e64 v73, v73, 0, vcc
	v_cndmask_b32_e64 v74, v74, 0, vcc
	v_cndmask_b32_e64 v75, v75, 0, vcc
	v_lshlrev_b32_e32 v10, 16, v72
	v_and_b32_e32 v11, 0xffff0000, v72
	v_lshlrev_b32_e32 v12, 16, v73
	v_and_b32_e32 v13, 0xffff0000, v73
	v_lshlrev_b32_e32 v14, 16, v74
	v_and_b32_e32 v15, 0xffff0000, v74
	v_lshlrev_b32_e32 v16, 16, v75
	v_and_b32_e32 v17, 0xffff0000, v75
	v_sub_f32_e32 v10, v10, v2
	v_sub_f32_e32 v11, v11, v3
	v_sub_f32_e32 v12, v12, v4
	v_sub_f32_e32 v13, v13, v5
	v_sub_f32_e32 v14, v14, v6
	v_sub_f32_e32 v15, v15, v7
	v_sub_f32_e32 v16, v16, v8
	v_sub_f32_e32 v17, v17, v9
	v_fmac_f32_e32 v2, v92, v10
	v_fmac_f32_e32 v3, v93, v11
	v_fmac_f32_e32 v4, v94, v12
	v_fmac_f32_e32 v5, v95, v13
	v_fmac_f32_e32 v6, v96, v14
	v_fmac_f32_e32 v7, v97, v15
	v_fmac_f32_e32 v8, v98, v16
	v_fmac_f32_e32 v9, v99, v17
	v_mul_f32_e32 v10, v124, v2
	v_mul_f32_e32 v11, v124, v3
	v_mul_f32_e32 v12, v124, v4
	v_mul_f32_e32 v13, v124, v5
	v_mul_f32_e32 v14, v124, v6
	v_mul_f32_e32 v15, v124, v7
	v_mul_f32_e32 v16, v124, v8
	v_mul_f32_e32 v17, v124, v9
	v_exp_f32_e32 v10, v10
	v_exp_f32_e32 v11, v11
	v_exp_f32_e32 v12, v12
	v_exp_f32_e32 v13, v13
	v_exp_f32_e32 v14, v14
	v_exp_f32_e32 v15, v15
	v_exp_f32_e32 v16, v16
	v_exp_f32_e32 v17, v17
	v_add_f32_e32 v10, 1.0, v10
	v_add_f32_e32 v11, 1.0, v11
	v_add_f32_e32 v12, 1.0, v12
	v_add_f32_e32 v13, 1.0, v13
	v_add_f32_e32 v14, 1.0, v14
	v_add_f32_e32 v15, 1.0, v15
	v_add_f32_e32 v16, 1.0, v16
	v_add_f32_e32 v17, 1.0, v17
	v_rcp_f32_e32 v10, v10
	v_rcp_f32_e32 v11, v11
	v_rcp_f32_e32 v12, v12
	v_rcp_f32_e32 v13, v13
	v_rcp_f32_e32 v14, v14
	v_rcp_f32_e32 v15, v15
	v_rcp_f32_e32 v16, v16
	v_rcp_f32_e32 v17, v17
	v_sub_u32_e32 v18, v44, v1
	v_cmp_gt_u32_e32 vcc, 8, v18
	v_fma_f32 v10, v128, v10, v132
	v_fma_f32 v11, v128, v11, v132
	v_fma_f32 v12, v128, v12, v132
	v_fma_f32 v13, v128, v13, v132
	v_fma_f32 v14, v128, v14, v132
	v_fma_f32 v15, v128, v15, v132
	v_fma_f32 v16, v128, v16, v132
	v_fma_f32 v17, v128, v17, v132
	v_cndmask_b32_e32 v10, v10, v2, vcc
	v_cndmask_b32_e32 v11, v11, v3, vcc
	v_cndmask_b32_e32 v12, v12, v4, vcc
	v_cndmask_b32_e32 v13, v13, v5, vcc
	v_cndmask_b32_e32 v14, v14, v6, vcc
	v_cndmask_b32_e32 v15, v15, v7, vcc
	v_cndmask_b32_e32 v16, v16, v8, vcc
	v_cndmask_b32_e32 v17, v17, v9, vcc
	v_cvt_pk_bf16_f32 v20, v10, v11
	v_cvt_pk_bf16_f32 v21, v12, v13
	v_cvt_pk_bf16_f32 v22, v14, v15
	v_cvt_pk_bf16_f32 v23, v16, v17
	v_cmp_gt_u32_e32 vcc, 36, v44
	v_cmp_gt_u32_e64 s[2:3], s33, v40
	s_and_b64 vcc, vcc, s[2:3]
	v_cndmask_b32_e32 v20, 0, v20, vcc
	v_cndmask_b32_e32 v21, 0, v21, vcc
	v_cndmask_b32_e32 v22, 0, v22, vcc
	v_cndmask_b32_e32 v23, 0, v23, vcc
	global_store_dwordx4 v52, v[20:23], s[18:19] sc1
	s_waitcnt vmcnt(5)
	v_lshlrev_b32_e32 v2, 16, v60
	v_and_b32_e32 v3, 0xffff0000, v60
	v_lshlrev_b32_e32 v4, 16, v61
	v_and_b32_e32 v5, 0xffff0000, v61
	v_lshlrev_b32_e32 v6, 16, v62
	v_and_b32_e32 v7, 0xffff0000, v62
	v_lshlrev_b32_e32 v8, 16, v63
	v_and_b32_e32 v9, 0xffff0000, v63
	v_and_b32_e32 v18, 0x7ff, v41
	v_cmp_eq_u32_e32 vcc, 0, v18
	s_nop 1
	v_cndmask_b32_e64 v76, v76, 0, vcc
	v_cndmask_b32_e64 v77, v77, 0, vcc
	v_cndmask_b32_e64 v78, v78, 0, vcc
	v_cndmask_b32_e64 v79, v79, 0, vcc
	v_lshlrev_b32_e32 v10, 16, v76
	v_and_b32_e32 v11, 0xffff0000, v76
	v_lshlrev_b32_e32 v12, 16, v77
	v_and_b32_e32 v13, 0xffff0000, v77
	v_lshlrev_b32_e32 v14, 16, v78
	v_and_b32_e32 v15, 0xffff0000, v78
	v_lshlrev_b32_e32 v16, 16, v79
	v_and_b32_e32 v17, 0xffff0000, v79
	v_sub_f32_e32 v10, v10, v2
	v_sub_f32_e32 v11, v11, v3
	v_sub_f32_e32 v12, v12, v4
	v_sub_f32_e32 v13, v13, v5
	v_sub_f32_e32 v14, v14, v6
	v_sub_f32_e32 v15, v15, v7
	v_sub_f32_e32 v16, v16, v8
	v_sub_f32_e32 v17, v17, v9
	v_fmac_f32_e32 v2, v100, v10
	v_fmac_f32_e32 v3, v101, v11
	v_fmac_f32_e32 v4, v102, v12
	v_fmac_f32_e32 v5, v103, v13
	v_fmac_f32_e32 v6, v104, v14
	v_fmac_f32_e32 v7, v105, v15
	v_fmac_f32_e32 v8, v106, v16
	v_fmac_f32_e32 v9, v107, v17
	v_mul_f32_e32 v10, v125, v2
	v_mul_f32_e32 v11, v125, v3
	v_mul_f32_e32 v12, v125, v4
	v_mul_f32_e32 v13, v125, v5
	v_mul_f32_e32 v14, v125, v6
	v_mul_f32_e32 v15, v125, v7
	v_mul_f32_e32 v16, v125, v8
	v_mul_f32_e32 v17, v125, v9
	v_exp_f32_e32 v10, v10
	v_exp_f32_e32 v11, v11
	v_exp_f32_e32 v12, v12
	v_exp_f32_e32 v13, v13
	v_exp_f32_e32 v14, v14
	v_exp_f32_e32 v15, v15
	v_exp_f32_e32 v16, v16
	v_exp_f32_e32 v17, v17
	v_add_f32_e32 v10, 1.0, v10
	v_add_f32_e32 v11, 1.0, v11
	v_add_f32_e32 v12, 1.0, v12
	v_add_f32_e32 v13, 1.0, v13
	v_add_f32_e32 v14, 1.0, v14
	v_add_f32_e32 v15, 1.0, v15
	v_add_f32_e32 v16, 1.0, v16
	v_add_f32_e32 v17, 1.0, v17
	v_rcp_f32_e32 v10, v10
	v_rcp_f32_e32 v11, v11
	v_rcp_f32_e32 v12, v12
	v_rcp_f32_e32 v13, v13
	v_rcp_f32_e32 v14, v14
	v_rcp_f32_e32 v15, v15
	v_rcp_f32_e32 v16, v16
	v_rcp_f32_e32 v17, v17
	v_sub_u32_e32 v18, v45, v1
	v_cmp_gt_u32_e32 vcc, 8, v18
	v_fma_f32 v10, v129, v10, v133
	v_fma_f32 v11, v129, v11, v133
	v_fma_f32 v12, v129, v12, v133
	v_fma_f32 v13, v129, v13, v133
	v_fma_f32 v14, v129, v14, v133
	v_fma_f32 v15, v129, v15, v133
	v_fma_f32 v16, v129, v16, v133
	v_fma_f32 v17, v129, v17, v133
	v_cndmask_b32_e32 v10, v10, v2, vcc
	v_cndmask_b32_e32 v11, v11, v3, vcc
	v_cndmask_b32_e32 v12, v12, v4, vcc
	v_cndmask_b32_e32 v13, v13, v5, vcc
	v_cndmask_b32_e32 v14, v14, v6, vcc
	v_cndmask_b32_e32 v15, v15, v7, vcc
	v_cndmask_b32_e32 v16, v16, v8, vcc
	v_cndmask_b32_e32 v17, v17, v9, vcc
	v_cvt_pk_bf16_f32 v20, v10, v11
	v_cvt_pk_bf16_f32 v21, v12, v13
	v_cvt_pk_bf16_f32 v22, v14, v15
	v_cvt_pk_bf16_f32 v23, v16, v17
	v_cmp_gt_u32_e32 vcc, 36, v45
	v_cmp_gt_u32_e64 s[2:3], s33, v41
	s_and_b64 vcc, vcc, s[2:3]
	v_cndmask_b32_e32 v20, 0, v20, vcc
	v_cndmask_b32_e32 v21, 0, v21, vcc
	v_cndmask_b32_e32 v22, 0, v22, vcc
	v_cndmask_b32_e32 v23, 0, v23, vcc
	global_store_dwordx4 v53, v[20:23], s[18:19] sc1
	s_waitcnt vmcnt(2)
	v_lshlrev_b32_e32 v2, 16, v64
	v_and_b32_e32 v3, 0xffff0000, v64
	v_lshlrev_b32_e32 v4, 16, v65
	v_and_b32_e32 v5, 0xffff0000, v65
	v_lshlrev_b32_e32 v6, 16, v66
	v_and_b32_e32 v7, 0xffff0000, v66
	v_lshlrev_b32_e32 v8, 16, v67
	v_and_b32_e32 v9, 0xffff0000, v67
	v_and_b32_e32 v18, 0x7ff, v42
	v_cmp_eq_u32_e32 vcc, 0, v18
	s_nop 1
	v_cndmask_b32_e64 v80, v80, 0, vcc
	v_cndmask_b32_e64 v81, v81, 0, vcc
	v_cndmask_b32_e64 v82, v82, 0, vcc
	v_cndmask_b32_e64 v83, v83, 0, vcc
	v_lshlrev_b32_e32 v10, 16, v80
	v_and_b32_e32 v11, 0xffff0000, v80
	v_lshlrev_b32_e32 v12, 16, v81
	v_and_b32_e32 v13, 0xffff0000, v81
	v_lshlrev_b32_e32 v14, 16, v82
	v_and_b32_e32 v15, 0xffff0000, v82
	v_lshlrev_b32_e32 v16, 16, v83
	v_and_b32_e32 v17, 0xffff0000, v83
	v_sub_f32_e32 v10, v10, v2
	v_sub_f32_e32 v11, v11, v3
	v_sub_f32_e32 v12, v12, v4
	v_sub_f32_e32 v13, v13, v5
	v_sub_f32_e32 v14, v14, v6
	v_sub_f32_e32 v15, v15, v7
	v_sub_f32_e32 v16, v16, v8
	v_sub_f32_e32 v17, v17, v9
	v_fmac_f32_e32 v2, v108, v10
	v_fmac_f32_e32 v3, v109, v11
	v_fmac_f32_e32 v4, v110, v12
	v_fmac_f32_e32 v5, v111, v13
	v_fmac_f32_e32 v6, v112, v14
	v_fmac_f32_e32 v7, v113, v15
	v_fmac_f32_e32 v8, v114, v16
	v_fmac_f32_e32 v9, v115, v17
	v_mul_f32_e32 v10, v126, v2
	v_mul_f32_e32 v11, v126, v3
	v_mul_f32_e32 v12, v126, v4
	v_mul_f32_e32 v13, v126, v5
	v_mul_f32_e32 v14, v126, v6
	v_mul_f32_e32 v15, v126, v7
	v_mul_f32_e32 v16, v126, v8
	v_mul_f32_e32 v17, v126, v9
	v_exp_f32_e32 v10, v10
	v_exp_f32_e32 v11, v11
	v_exp_f32_e32 v12, v12
	v_exp_f32_e32 v13, v13
	v_exp_f32_e32 v14, v14
	v_exp_f32_e32 v15, v15
	v_exp_f32_e32 v16, v16
	v_exp_f32_e32 v17, v17
	v_add_f32_e32 v10, 1.0, v10
	v_add_f32_e32 v11, 1.0, v11
	v_add_f32_e32 v12, 1.0, v12
	v_add_f32_e32 v13, 1.0, v13
	v_add_f32_e32 v14, 1.0, v14
	v_add_f32_e32 v15, 1.0, v15
	v_add_f32_e32 v16, 1.0, v16
	v_add_f32_e32 v17, 1.0, v17
	v_rcp_f32_e32 v10, v10
	v_rcp_f32_e32 v11, v11
	v_rcp_f32_e32 v12, v12
	v_rcp_f32_e32 v13, v13
	v_rcp_f32_e32 v14, v14
	v_rcp_f32_e32 v15, v15
	v_rcp_f32_e32 v16, v16
	v_rcp_f32_e32 v17, v17
	v_sub_u32_e32 v18, v46, v1
	v_cmp_gt_u32_e32 vcc, 8, v18
	v_fma_f32 v10, v130, v10, v134
	v_fma_f32 v11, v130, v11, v134
	v_fma_f32 v12, v130, v12, v134
	v_fma_f32 v13, v130, v13, v134
	v_fma_f32 v14, v130, v14, v134
	v_fma_f32 v15, v130, v15, v134
	v_fma_f32 v16, v130, v16, v134
	v_fma_f32 v17, v130, v17, v134
	v_cndmask_b32_e32 v10, v10, v2, vcc
	v_cndmask_b32_e32 v11, v11, v3, vcc
	v_cndmask_b32_e32 v12, v12, v4, vcc
	v_cndmask_b32_e32 v13, v13, v5, vcc
	v_cndmask_b32_e32 v14, v14, v6, vcc
	v_cndmask_b32_e32 v15, v15, v7, vcc
	v_cndmask_b32_e32 v16, v16, v8, vcc
	v_cndmask_b32_e32 v17, v17, v9, vcc
	v_cvt_pk_bf16_f32 v20, v10, v11
	v_cvt_pk_bf16_f32 v21, v12, v13
	v_cvt_pk_bf16_f32 v22, v14, v15
	v_cvt_pk_bf16_f32 v23, v16, v17
	v_cmp_gt_u32_e32 vcc, 36, v46
	v_cmp_gt_u32_e64 s[2:3], s33, v42
	s_and_b64 vcc, vcc, s[2:3]
	v_cndmask_b32_e32 v20, 0, v20, vcc
	v_cndmask_b32_e32 v21, 0, v21, vcc
	v_cndmask_b32_e32 v22, 0, v22, vcc
	v_cndmask_b32_e32 v23, 0, v23, vcc
	global_store_dwordx4 v54, v[20:23], s[18:19] sc1
	s_cmp_ge_u32 s28, 24
	s_cbranch_scc1 .Llin_s3
	s_waitcnt vmcnt(3)
	v_lshlrev_b32_e32 v2, 16, v68
	v_and_b32_e32 v3, 0xffff0000, v68
	v_lshlrev_b32_e32 v4, 16, v69
	v_and_b32_e32 v5, 0xffff0000, v69
	v_lshlrev_b32_e32 v6, 16, v70
	v_and_b32_e32 v7, 0xffff0000, v70
	v_lshlrev_b32_e32 v8, 16, v71
	v_and_b32_e32 v9, 0xffff0000, v71
	v_mov_b32_e32 v10, v84
	v_mov_b32_e32 v11, v85
	v_mov_b32_e32 v12, v86
	v_mov_b32_e32 v13, v87
	v_mov_b32_e32 v14, v88
	v_mov_b32_e32 v15, v89
	v_mov_b32_e32 v16, v90
	v_mov_b32_e32 v17, v91
	v_sub_f32_e32 v10, v10, v2
	v_sub_f32_e32 v11, v11, v3
	v_sub_f32_e32 v12, v12, v4
	v_sub_f32_e32 v13, v13, v5
	v_sub_f32_e32 v14, v14, v6
	v_sub_f32_e32 v15, v15, v7
	v_sub_f32_e32 v16, v16, v8
	v_sub_f32_e32 v17, v17, v9
	v_fmac_f32_e32 v2, v116, v10
	v_fmac_f32_e32 v3, v117, v11
	v_fmac_f32_e32 v4, v118, v12
	v_fmac_f32_e32 v5, v119, v13
	v_fmac_f32_e32 v6, v120, v14
	v_fmac_f32_e32 v7, v121, v15
	v_fmac_f32_e32 v8, v122, v16
	v_fmac_f32_e32 v9, v123, v17
	v_mul_f32_e32 v10, v127, v2
	v_mul_f32_e32 v11, v127, v3
	v_mul_f32_e32 v12, v127, v4
	v_mul_f32_e32 v13, v127, v5
	v_mul_f32_e32 v14, v127, v6
	v_mul_f32_e32 v15, v127, v7
	v_mul_f32_e32 v16, v127, v8
	v_mul_f32_e32 v17, v127, v9
	v_exp_f32_e32 v10, v10
	v_exp_f32_e32 v11, v11
	v_exp_f32_e32 v12, v12
	v_exp_f32_e32 v13, v13
	v_exp_f32_e32 v14, v14
	v_exp_f32_e32 v15, v15
	v_exp_f32_e32 v16, v16
	v_exp_f32_e32 v17, v17
	v_add_f32_e32 v10, 1.0, v10
	v_add_f32_e32 v11, 1.0, v11
	v_add_f32_e32 v12, 1.0, v12
	v_add_f32_e32 v13, 1.0, v13
	v_add_f32_e32 v14, 1.0, v14
	v_add_f32_e32 v15, 1.0, v15
	v_add_f32_e32 v16, 1.0, v16
	v_add_f32_e32 v17, 1.0, v17
	v_rcp_f32_e32 v10, v10
	v_rcp_f32_e32 v11, v11
	v_rcp_f32_e32 v12, v12
	v_rcp_f32_e32 v13, v13
	v_rcp_f32_e32 v14, v14
	v_rcp_f32_e32 v15, v15
	v_rcp_f32_e32 v16, v16
	v_rcp_f32_e32 v17, v17
	v_sub_u32_e32 v18, v47, v1
	v_cmp_gt_u32_e32 vcc, 8, v18
	v_fma_f32 v10, v131, v10, v135
	v_fma_f32 v11, v131, v11, v135
	v_fma_f32 v12, v131, v12, v135
	v_fma_f32 v13, v131, v13, v135
	v_fma_f32 v14, v131, v14, v135
	v_fma_f32 v15, v131, v15, v135
	v_fma_f32 v16, v131, v16, v135
	v_fma_f32 v17, v131, v17, v135
	v_cndmask_b32_e32 v10, v10, v2, vcc
	v_cndmask_b32_e32 v11, v11, v3, vcc
	v_cndmask_b32_e32 v12, v12, v4, vcc
	v_cndmask_b32_e32 v13, v13, v5, vcc
	v_cndmask_b32_e32 v14, v14, v6, vcc
	v_cndmask_b32_e32 v15, v15, v7, vcc
	v_cndmask_b32_e32 v16, v16, v8, vcc
	v_cndmask_b32_e32 v17, v17, v9, vcc
	v_cvt_pk_bf16_f32 v20, v10, v11
	v_cvt_pk_bf16_f32 v21, v12, v13
	v_cvt_pk_bf16_f32 v22, v14, v15
	v_cvt_pk_bf16_f32 v23, v16, v17
	v_cmp_gt_u32_e32 vcc, 36, v47
	v_cmp_gt_u32_e64 s[2:3], s33, v43
	s_and_b64 vcc, vcc, s[2:3]
	v_cndmask_b32_e32 v20, 0, v20, vcc
	v_cndmask_b32_e32 v21, 0, v21, vcc
	v_cndmask_b32_e32 v22, 0, v22, vcc
	v_cndmask_b32_e32 v23, 0, v23, vcc
	global_store_dwordx4 v55, v[20:23], s[18:19] sc1
